# r17 + solve skips rows 16..63 for 16-token sample items (those rows are structurally zero: beta=0), saving most of the last item's solve on the 64 WGs that run 17 items
# speedup vs baseline: 1.0043x; 1.0040x over previous
.LBB0_837:
	s_sub_i32 s98, s2, s46
	s_cmpk_lt_i32 s98, 0x1000
	s_cbranch_scc1 .Lsolve_full
	s_waitcnt lgkmcnt(0)
	v_mov_b32_e32 v36, 0
	v_mov_b32_e32 v37, 0
	v_mov_b32_e32 v38, 0
	v_mov_b32_e32 v39, 0
	v_mov_b32_e32 v40, 0
	v_mov_b32_e32 v41, 0
	v_mov_b32_e32 v42, 0
	v_mov_b32_e32 v43, 0
	v_mov_b32_e32 v44, 0
	v_mov_b32_e32 v45, 0
	v_mov_b32_e32 v46, 0
	v_mov_b32_e32 v47, 0
	v_mov_b32_e32 v48, 0
	v_mov_b32_e32 v49, 0
	v_mov_b32_e32 v50, 0
	v_mov_b32_e32 v51, 0
	v_mov_b32_e32 v52, 0
	v_mov_b32_e32 v53, 0
	v_mov_b32_e32 v54, 0
	v_mov_b32_e32 v55, 0
	v_mov_b32_e32 v56, 0
	v_mov_b32_e32 v57, 0
	v_mov_b32_e32 v58, 0
	v_mov_b32_e32 v59, 0
	v_mov_b32_e32 v60, 0
	v_mov_b32_e32 v61, 0
	v_mov_b32_e32 v62, 0
	v_mov_b32_e32 v63, 0
	v_mov_b32_e32 v64, 0
	v_mov_b32_e32 v65, 0
	v_mov_b32_e32 v66, 0
	v_mov_b32_e32 v67, 0
	v_mov_b32_e32 v68, 0
	v_mov_b32_e32 v69, 0
	v_mov_b32_e32 v70, 0
	v_mov_b32_e32 v71, 0
	v_mov_b32_e32 v72, 0
	v_mov_b32_e32 v73, 0
	v_mov_b32_e32 v74, 0
	v_mov_b32_e32 v75, 0
	v_mov_b32_e32 v76, 0
	v_mov_b32_e32 v77, 0
	v_mov_b32_e32 v78, 0
	v_mov_b32_e32 v79, 0
	v_mov_b32_e32 v80, 0
	v_mov_b32_e32 v81, 0
	v_mov_b32_e32 v82, 0
	v_mov_b32_e32 v11, 0
	s_branch .Lsolve_done

.Lsolve_done:
	s_and_saveexec_b64 s[0:1], s[16:17]
	s_xor_b64 s[0:1], exec, s[0:1]
	s_cbranch_execz .LBB0_941
	v_lshl_add_u64 v[84:85], v[22:23], 1, s[70:71]
	v_add_co_u32_e32 v88, vcc, 0x4000, v84
	v_cvt_pk_bf16_f32 v2, v2, s0
	s_mov_b64 s[24:25], 0x4000
	v_addc_co_u32_e32 v89, vcc, 0, v85, vcc
	v_lshl_add_u64 v[86:87], v[84:85], 0, s[24:25]
	global_store_short v[88:89], v2, off
	v_cvt_pk_bf16_f32 v2, v3, s0
	global_store_short v[86:87], v2, off offset:256
	v_cvt_pk_bf16_f32 v2, v4, s0
	global_store_short v[86:87], v2, off offset:512
	v_cvt_pk_bf16_f32 v2, v5, s0
	global_store_short v[86:87], v2, off offset:768
	v_cvt_pk_bf16_f32 v2, v6, s0
	global_store_short v[86:87], v2, off offset:1024
	v_cvt_pk_bf16_f32 v2, v7, s0
	global_store_short v[86:87], v2, off offset:1280
	v_cvt_pk_bf16_f32 v2, v8, s0
	global_store_short v[86:87], v2, off offset:1536
	v_cvt_pk_bf16_f32 v2, v9, s0
	global_store_short v[86:87], v2, off offset:1792
	v_cvt_pk_bf16_f32 v2, v10, s0
	global_store_short v[86:87], v2, off offset:2048
	v_cvt_pk_bf16_f32 v2, v12, s0
	global_store_short v[86:87], v2, off offset:2304
	v_cvt_pk_bf16_f32 v2, v13, s0
	global_store_short v[86:87], v2, off offset:2560
	v_cvt_pk_bf16_f32 v2, v14, s0
	global_store_short v[86:87], v2, off offset:2816
	v_cvt_pk_bf16_f32 v2, v17, s0
	global_store_short v[86:87], v2, off offset:3072
	v_cvt_pk_bf16_f32 v2, v19, s0
	global_store_short v[86:87], v2, off offset:3328
	v_cvt_pk_bf16_f32 v2, v28, s0
	global_store_short v[86:87], v2, off offset:3584
	v_cvt_pk_bf16_f32 v2, v35, s0
	s_movk_i32 s24, 0x5000
	global_store_short v[86:87], v2, off offset:3840
	v_add_co_u32_e32 v2, vcc, s24, v84
	s_movk_i32 s24, 0x6000
	s_nop 0
	v_addc_co_u32_e32 v3, vcc, 0, v85, vcc
	v_add_co_u32_e32 v4, vcc, s24, v84
	v_cvt_pk_bf16_f32 v6, v36, s0
	s_nop 0
	v_addc_co_u32_e32 v5, vcc, 0, v85, vcc
	global_store_short v[4:5], v6, off offset:-4096
	v_cvt_pk_bf16_f32 v6, v37, s0
	global_store_short v[2:3], v6, off offset:256
	v_cvt_pk_bf16_f32 v6, v38, s0
	global_store_short v[2:3], v6, off offset:512
	v_cvt_pk_bf16_f32 v6, v39, s0
	global_store_short v[2:3], v6, off offset:768
	v_cvt_pk_bf16_f32 v6, v40, s0
	global_store_short v[2:3], v6, off offset:1024
	v_cvt_pk_bf16_f32 v6, v41, s0
	global_store_short v[2:3], v6, off offset:1280
	v_cvt_pk_bf16_f32 v6, v42, s0
	global_store_short v[2:3], v6, off offset:1536
	v_cvt_pk_bf16_f32 v6, v43, s0
	global_store_short v[2:3], v6, off offset:1792
	v_cvt_pk_bf16_f32 v6, v44, s0
	global_store_short v[2:3], v6, off offset:2048
	v_cvt_pk_bf16_f32 v6, v45, s0
	global_store_short v[2:3], v6, off offset:2304
	v_cvt_pk_bf16_f32 v6, v46, s0
	global_store_short v[2:3], v6, off offset:2560
	v_cvt_pk_bf16_f32 v6, v47, s0
	global_store_short v[2:3], v6, off offset:2816
	v_cvt_pk_bf16_f32 v6, v48, s0
	global_store_short v[2:3], v6, off offset:3072
	v_cvt_pk_bf16_f32 v6, v49, s0
	global_store_short v[2:3], v6, off offset:3328
	v_cvt_pk_bf16_f32 v6, v50, s0
	global_store_short v[2:3], v6, off offset:3584
	v_cvt_pk_bf16_f32 v6, v51, s0
	global_store_short v[2:3], v6, off offset:3840
	v_cvt_pk_bf16_f32 v2, v52, s0
	global_store_short v[4:5], v2, off
	v_cvt_pk_bf16_f32 v2, v53, s0
	global_store_short v[4:5], v2, off offset:256
	v_cvt_pk_bf16_f32 v2, v54, s0
	global_store_short v[4:5], v2, off offset:512
	v_cvt_pk_bf16_f32 v2, v55, s0
	global_store_short v[4:5], v2, off offset:768
	v_cvt_pk_bf16_f32 v2, v56, s0
	global_store_short v[4:5], v2, off offset:1024
	v_cvt_pk_bf16_f32 v2, v57, s0
	global_store_short v[4:5], v2, off offset:1280
	v_cvt_pk_bf16_f32 v2, v58, s0
	global_store_short v[4:5], v2, off offset:1536
	v_cvt_pk_bf16_f32 v2, v59, s0
	global_store_short v[4:5], v2, off offset:1792
	v_cvt_pk_bf16_f32 v2, v60, s0
	global_store_short v[4:5], v2, off offset:2048
	v_cvt_pk_bf16_f32 v2, v61, s0
	global_store_short v[4:5], v2, off offset:2304
	v_cvt_pk_bf16_f32 v2, v62, s0
	global_store_short v[4:5], v2, off offset:2560
	v_cvt_pk_bf16_f32 v2, v63, s0
	global_store_short v[4:5], v2, off offset:2816
	v_cvt_pk_bf16_f32 v2, v64, s0
	global_store_short v[4:5], v2, off offset:3072
	v_cvt_pk_bf16_f32 v2, v65, s0
	global_store_short v[4:5], v2, off offset:3328
	v_cvt_pk_bf16_f32 v2, v66, s0
	global_store_short v[4:5], v2, off offset:3584
	v_cvt_pk_bf16_f32 v2, v67, s0
	s_movk_i32 s24, 0x7000
	global_store_short v[4:5], v2, off offset:3840
	v_add_co_u32_e32 v2, vcc, s24, v84
	v_cvt_pk_bf16_f32 v4, v68, s0
	s_nop 0
	v_addc_co_u32_e32 v3, vcc, 0, v85, vcc
	global_store_short v[2:3], v4, off
	v_cvt_pk_bf16_f32 v4, v69, s0
	global_store_short v[2:3], v4, off offset:256
	v_cvt_pk_bf16_f32 v4, v70, s0
	global_store_short v[2:3], v4, off offset:512
	v_cvt_pk_bf16_f32 v4, v71, s0
	global_store_short v[2:3], v4, off offset:768
	v_cvt_pk_bf16_f32 v4, v72, s0
	global_store_short v[2:3], v4, off offset:1024
	v_cvt_pk_bf16_f32 v4, v73, s0
	global_store_short v[2:3], v4, off offset:1280
	v_cvt_pk_bf16_f32 v4, v74, s0
	global_store_short v[2:3], v4, off offset:1536
	v_cvt_pk_bf16_f32 v4, v75, s0
	global_store_short v[2:3], v4, off offset:1792
	v_cvt_pk_bf16_f32 v4, v76, s0
	global_store_short v[2:3], v4, off offset:2048
	v_cvt_pk_bf16_f32 v4, v77, s0
	global_store_short v[2:3], v4, off offset:2304
	v_cvt_pk_bf16_f32 v4, v78, s0
	global_store_short v[2:3], v4, off offset:2560
	v_cvt_pk_bf16_f32 v4, v79, s0
	global_store_short v[2:3], v4, off offset:2816
	v_cvt_pk_bf16_f32 v4, v80, s0
	global_store_short v[2:3], v4, off offset:3072
	v_cvt_pk_bf16_f32 v4, v81, s0
	global_store_short v[2:3], v4, off offset:3328
	v_cvt_pk_bf16_f32 v4, v82, s0
	global_store_short v[2:3], v4, off offset:3584
	v_cvt_pk_bf16_f32 v4, v11, s0
	global_store_short v[2:3], v4, off offset:3840
	s_andn2_saveexec_b64 s[0:1], s[0:1]
	s_cbranch_execnz .LBB0_942
